# comb10 + phase-A tile-start offsets rebalanced (Q +192, K +96) so no workgroup gets more than 12 tiles
# baseline (speedup 1.0000x reference)
;     __device__ __forceinline__ bool next(int i, Unit& u) const {
;         const long L = (long)i * G + c; if (L >= nwg) return false;
;         int w = (int)L; { const int q = nwg / NXCD, r = nwg % NXCD, xcd = w % NXCD, off = w / NXCD; w = (xcd < r ? xcd * (q + 1) : r * (q + 1) + (xcd - r) * q) + off; }
;         u.pb = w / per; w -= u.pb * per;
;         const int nig = WGM * nN, gid = w / nig, fm = gid * WGM, gsz = (nM - fm) < WGM ? (nM - fm) : WGM;
;         u.pm = fm + ((w % nig) % gsz); u.pn = (w % nig) / gsz; return true;
;     }
; template <int PH> __device__ __forceinline__ void phase_body(const Args& args, LAS unsigned char* lds) {
;     ...
;                 if (EN(11)) { pg8::Gemm g{PB, WS + l * 1024, (long)NT * INP, 0, INP, 256, NB, l == 0 ? 9 : 8, 3};
;                   pg8::EpiQK<true> E{QB, 192, STAT, COST, SINT}; pg8::gemm_phase(lds, g, G, (bx + 64) % G, E); }
.LBB0_375:
	s_abs_i32 s68, s27
	v_cvt_f32_u32_e32 v2, s68
	s_sub_i32 s4, 0, s68
	s_add_i32 s2, s26, 0xc0
	s_ashr_i32 s3, s2, 31
	v_rcp_iflag_f32_e32 v2, v2
	s_abs_i32 s2, s2
	v_mov_b32_e32 v10, v1
	v_mul_f32_e32 v2, 0x4f7ffffe, v2
	v_cvt_u32_f32_e32 v2, v2
	s_nop 0
	v_readfirstlane_b32 s34, v2
	s_mul_i32 s4, s4, s34
	s_mul_hi_u32 s4, s34, s4
	s_add_i32 s34, s34, s4
	s_mul_hi_u32 s4, s2, s34
	s_mul_i32 s4, s4, s68
	s_sub_i32 s2, s2, s4
	s_sub_i32 s4, s2, s68
	s_cmp_ge_u32 s2, s68
	s_cselect_b32 s2, s4, s2
	s_sub_i32 s4, s2, s68
	s_cmp_ge_u32 s2, s68
	s_cselect_b32 s2, s4, s2
	s_xor_b32 s2, s2, s3
	s_sub_i32 s35, s2, s3
	s_ashr_i32 s69, s35, 31
	s_cmpk_lt_i32 s35, 0x360
	s_cselect_b64 s[2:3], -1, 0
	s_cmpk_gt_i32 s35, 0x35f
	v_readfirstlane_b32 s4, v10
	s_cbranch_scc1 .LBB0_377
	s_ashr_i32 s5, s35, 31
	s_lshr_b32 s5, s5, 29
	s_add_i32 s5, s35, s5
	s_ashr_i32 s6, s5, 3
	s_and_b32 s5, s5, -8
	s_sub_i32 s5, s35, s5
	s_lshr_b32 s7, s5, 31
	s_or_b32 s7, s7, 0x6c
	s_mul_i32 s5, s7, s5
	s_add_i32 s5, s5, s6
	s_mul_hi_i32 s6, s5, 0x4bda12f7
	s_lshr_b32 s7, s6, 31
	s_ashr_i32 s6, s6, 3
	s_add_i32 s95, s6, s7
	s_mul_i32 s6, s95, 0xffffffe5
	s_add_i32 s6, s6, s5
	s_mul_hi_i32 s5, s6, 0x2aaaaaab
	s_lshr_b32 s7, s5, 31
	s_ashr_i32 s5, s5, 2
	s_add_i32 s5, s5, s7
	s_lshl_b32 s7, s5, 3
	s_sub_i32 s8, 9, s7
	s_min_i32 s8, s8, 8
	s_abs_i32 s9, s8
	v_cvt_f32_u32_e32 v2, s9
	s_sub_i32 s11, 0, s9
	s_mul_i32 s5, s5, 24
	s_sub_i32 s5, s6, s5
	v_rcp_iflag_f32_e32 v2, v2
	s_abs_i32 s6, s5
	s_xor_b32 s10, s5, s8
	s_ashr_i32 s10, s10, 31
	v_mul_f32_e32 v2, 0x4f7ffffe, v2
	v_cvt_u32_f32_e32 v2, v2
	s_nop 0
	v_readfirstlane_b32 s12, v2
	s_mul_i32 s11, s11, s12
	s_mul_hi_u32 s11, s12, s11
	s_add_i32 s12, s12, s11
	s_mul_hi_u32 s11, s6, s12
	s_mul_i32 s12, s11, s9
	s_sub_i32 s6, s6, s12
	s_add_i32 s12, s11, 1
	s_sub_i32 s13, s6, s9
	s_cmp_ge_u32 s6, s9
	s_cselect_b32 s11, s12, s11
	s_cselect_b32 s6, s13, s6
	s_add_i32 s12, s11, 1
	s_cmp_ge_u32 s6, s9
	s_cselect_b32 s6, s12, s11
	s_xor_b32 s6, s6, s10
	s_sub_i32 s96, s6, s10
	s_mul_i32 s6, s96, s8
	s_sub_i32 s5, s5, s6
	s_add_i32 s97, s5, s7

;     __device__ __forceinline__ bool next(int i, Unit& u) const {
;         const long L = (long)i * G + c; if (L >= nwg) return false;
;         int w = (int)L; { const int q = nwg / NXCD, r = nwg % NXCD, xcd = w % NXCD, off = w / NXCD; w = (xcd < r ? xcd * (q + 1) : r * (q + 1) + (xcd - r) * q) + off; }
;         u.pb = w / per; w -= u.pb * per;
;         const int nig = WGM * nN, gid = w / nig, fm = gid * WGM, gsz = (nM - fm) < WGM ? (nM - fm) : WGM;
;         u.pm = fm + ((w % nig) % gsz); u.pn = (w % nig) / gsz; return true;
;     }
; template <int PH> __device__ __forceinline__ void phase_body(const Args& args, LAS unsigned char* lds) {
;     ...
;                 if (EN(12)) { pg8::Gemm g{PB + O_CKV, WS + l * 1024 + 256, (long)NT * INP, 0, INP, 256, NB, 9, 3};
;                   pg8::EpiQK<false> E{KB, KP, STAT, COST, SINT}; pg8::gemm_phase(lds, g, G, (bx + 160) % G, E); }
.LBB0_461:
	s_add_i32 s2, s26, 0x60
	s_ashr_i32 s3, s2, 31
	s_abs_i32 s2, s2
	s_mul_hi_u32 s4, s2, s34
	s_mul_i32 s4, s4, s68
	s_sub_i32 s2, s2, s4
	s_sub_i32 s4, s2, s68
	s_cmp_ge_u32 s2, s68
	s_cselect_b32 s2, s4, s2
	s_sub_i32 s4, s2, s68
	s_cmp_ge_u32 s2, s68
	s_cselect_b32 s2, s4, s2
	s_xor_b32 s2, s2, s3
	s_sub_i32 s81, s2, s3
	s_ashr_i32 s82, s81, 31
	v_mov_b32_e32 v10, v1
	s_cmpk_lt_i32 s81, 0x360
	s_cselect_b64 s[2:3], -1, 0
	s_cmpk_gt_i32 s81, 0x35f
	v_readfirstlane_b32 s4, v10
	s_cbranch_scc1 .LBB0_463
	s_ashr_i32 s5, s81, 31
	s_lshr_b32 s5, s5, 29
	s_add_i32 s5, s81, s5
	s_ashr_i32 s6, s5, 3
	s_and_b32 s5, s5, -8
	s_sub_i32 s5, s81, s5
	s_cmp_lt_i32 s5, 0
	s_movk_i32 s7, 0x6d
	s_cselect_b32 s7, s7, 0x6c
	s_mul_i32 s5, s7, s5
	s_add_i32 s5, s5, s6
	s_mul_hi_i32 s6, s5, 0x4bda12f7
	s_lshr_b32 s7, s6, 31
	s_ashr_i32 s6, s6, 3
	s_add_i32 s15, s6, s7
	s_mul_i32 s6, s15, 0xffffffe5
	s_add_i32 s6, s6, s5
	s_mul_hi_i32 s5, s6, 0x2aaaaaab
	s_lshr_b32 s7, s5, 31
	s_ashr_i32 s5, s5, 2
	s_add_i32 s5, s5, s7
	s_lshl_b32 s7, s5, 3
	s_sub_i32 s8, 9, s7
	s_min_i32 s8, s8, 8
	s_abs_i32 s9, s8
	v_cvt_f32_u32_e32 v2, s9
	s_sub_i32 s11, 0, s9
	s_mul_i32 s5, s5, 24
	s_sub_i32 s5, s6, s5
	v_rcp_iflag_f32_e32 v2, v2
	s_abs_i32 s10, s5
	s_xor_b32 s6, s5, s8
	s_ashr_i32 s6, s6, 31
	v_mul_f32_e32 v2, 0x4f7ffffe, v2
	v_cvt_u32_f32_e32 v2, v2
	s_nop 0
	v_readfirstlane_b32 s14, v2
	s_mul_i32 s11, s11, s14
	s_mul_hi_u32 s11, s14, s11
	s_add_i32 s14, s14, s11
	s_mul_hi_u32 s11, s10, s14
	s_mul_i32 s14, s11, s9
	s_sub_i32 s10, s10, s14
	s_add_i32 s14, s11, 1
	s_sub_i32 s20, s10, s9
	s_cmp_ge_u32 s10, s9
	s_cselect_b32 s11, s14, s11
	s_cselect_b32 s10, s20, s10
	s_add_i32 s14, s11, 1
	s_cmp_ge_u32 s10, s9
	s_cselect_b32 s9, s14, s11
	s_xor_b32 s9, s9, s6
	s_sub_i32 s68, s9, s6
	s_mul_i32 s6, s68, s8
	s_sub_i32 s5, s5, s6
	s_add_i32 s69, s5, s7

;     __device__ __forceinline__ bool next(int i, Unit& u) const {
;         const long L = (long)i * G + c; if (L >= nwg) return false;
;         int w = (int)L; { const int q = nwg / NXCD, r = nwg % NXCD, xcd = w % NXCD, off = w / NXCD; w = (xcd < r ? xcd * (q + 1) : r * (q + 1) + (xcd - r) * q) + off; }
;         u.pb = w / per; w -= u.pb * per;
;         const int nig = WGM * nN, gid = w / nig, fm = gid * WGM, gsz = (nM - fm) < WGM ? (nM - fm) : WGM;
;         u.pm = fm + ((w % nig) % gsz); u.pn = (w % nig) / gsz; return true;
;     }
; template <int PH> __device__ __forceinline__ void phase_body(const Args& args, LAS unsigned char* lds) {
;     ...
;                 if (EN(11)) { pg8::Gemm g{PB, WS + l * 1024, (long)NT * INP, 0, INP, 256, NB, l == 0 ? 9 : 8, 3};
;                   pg8::EpiQK<true> E{QB, 192, STAT, COST, SINT}; pg8::gemm_phase(lds, g, G, (bx + 64) % G, E); }
.LBB0_1436:
	s_abs_i32 s56, s27
	v_cvt_f32_u32_e32 v2, s56
	s_sub_i32 s4, 0, s56
	s_add_i32 s2, s26, 0xc0
	s_ashr_i32 s3, s2, 31
	v_rcp_iflag_f32_e32 v2, v2
	s_abs_i32 s2, s2
	v_mov_b32_e32 v10, v1
	v_mul_f32_e32 v2, 0x4f7ffffe, v2
	v_cvt_u32_f32_e32 v2, v2
	s_nop 0
	v_readfirstlane_b32 s34, v2
	s_mul_i32 s4, s4, s34
	s_mul_hi_u32 s4, s34, s4
	s_add_i32 s34, s34, s4
	s_mul_hi_u32 s4, s2, s34
	s_mul_i32 s4, s4, s56
	s_sub_i32 s2, s2, s4
	s_sub_i32 s4, s2, s56
	s_cmp_ge_u32 s2, s56
	s_cselect_b32 s2, s4, s2
	s_sub_i32 s4, s2, s56
	s_cmp_ge_u32 s2, s56
	s_cselect_b32 s2, s4, s2
	s_xor_b32 s2, s2, s3
	s_sub_i32 s35, s2, s3
	s_ashr_i32 s57, s35, 31
	s_cmpk_lt_i32 s35, 0x300
	s_cselect_b64 s[2:3], -1, 0
	s_cmpk_gt_i32 s35, 0x2ff
	v_readfirstlane_b32 s4, v10
	s_cbranch_scc1 .LBB0_1438
	s_ashr_i32 s5, s35, 31
	s_lshr_b32 s5, s5, 29
	s_add_i32 s5, s35, s5
	s_ashr_i32 s6, s5, 3
	s_and_b32 s5, s5, -8
	s_sub_i32 s5, s35, s5
	s_lshr_b32 s7, s5, 31
	s_or_b32 s7, s7, 0x60
	s_mul_i32 s5, s7, s5
	s_add_i32 s5, s5, s6
	s_mul_hi_i32 s6, s5, 0x2aaaaaab
	s_lshr_b32 s7, s6, 31
	s_ashr_i32 s6, s6, 2
	s_add_i32 s90, s6, s7
	s_mul_i32 s6, s90, 0xffffffe8
	s_add_i32 s6, s6, s5
	s_mul_hi_i32 s5, s6, 0x2aaaaaab
	s_lshr_b32 s7, s5, 31
	s_ashr_i32 s5, s5, 2
	s_add_i32 s5, s5, s7
	s_lshl_b32 s7, s5, 3
	s_sub_i32 s8, 8, s7
	s_min_i32 s8, s8, 8
	s_abs_i32 s9, s8
	v_cvt_f32_u32_e32 v2, s9
	s_sub_i32 s11, 0, s9
	s_mul_i32 s5, s5, 24
	s_sub_i32 s5, s6, s5
	v_rcp_iflag_f32_e32 v2, v2
	s_abs_i32 s6, s5
	s_xor_b32 s10, s5, s8
	s_ashr_i32 s10, s10, 31
	v_mul_f32_e32 v2, 0x4f7ffffe, v2
	v_cvt_u32_f32_e32 v2, v2
	s_nop 0
	v_readfirstlane_b32 s12, v2
	s_mul_i32 s11, s11, s12
	s_mul_hi_u32 s11, s12, s11
	s_add_i32 s12, s12, s11
	s_mul_hi_u32 s11, s6, s12
	s_mul_i32 s12, s11, s9
	s_sub_i32 s6, s6, s12
	s_add_i32 s12, s11, 1
	s_sub_i32 s13, s6, s9
	s_cmp_ge_u32 s6, s9
	s_cselect_b32 s11, s12, s11
	s_cselect_b32 s6, s13, s6
	s_add_i32 s12, s11, 1
	s_cmp_ge_u32 s6, s9
	s_cselect_b32 s6, s12, s11
	s_xor_b32 s6, s6, s10
	s_sub_i32 s91, s6, s10
	s_mul_i32 s6, s91, s8
	s_sub_i32 s5, s5, s6
	s_add_i32 s92, s5, s7

;     __device__ __forceinline__ bool next(int i, Unit& u) const {
;         const long L = (long)i * G + c; if (L >= nwg) return false;
;         int w = (int)L; { const int q = nwg / NXCD, r = nwg % NXCD, xcd = w % NXCD, off = w / NXCD; w = (xcd < r ? xcd * (q + 1) : r * (q + 1) + (xcd - r) * q) + off; }
;         u.pb = w / per; w -= u.pb * per;
;         const int nig = WGM * nN, gid = w / nig, fm = gid * WGM, gsz = (nM - fm) < WGM ? (nM - fm) : WGM;
;         u.pm = fm + ((w % nig) % gsz); u.pn = (w % nig) / gsz; return true;
;     }
; template <int PH> __device__ __forceinline__ void phase_body(const Args& args, LAS unsigned char* lds) {
;     ...
;                 if (EN(12)) { pg8::Gemm g{PB + O_CKV, WS + l * 1024 + 256, (long)NT * INP, 0, INP, 256, NB, 9, 3};
;                   pg8::EpiQK<false> E{KB, KP, STAT, COST, SINT}; pg8::gemm_phase(lds, g, G, (bx + 160) % G, E); }
.LBB0_1522:
	s_add_i32 s2, s26, 0x60
	s_ashr_i32 s3, s2, 31
	s_abs_i32 s2, s2
	s_mul_hi_u32 s4, s2, s34
	s_mul_i32 s4, s4, s56
	s_sub_i32 s2, s2, s4
	s_sub_i32 s4, s2, s56
	s_cmp_ge_u32 s2, s56
	s_cselect_b32 s2, s4, s2
	s_sub_i32 s4, s2, s56
	s_cmp_ge_u32 s2, s56
	s_cselect_b32 s2, s4, s2
	s_xor_b32 s2, s2, s3
	s_sub_i32 s68, s2, s3
	s_ashr_i32 s69, s68, 31
	v_mov_b32_e32 v10, v1
	s_cmpk_lt_i32 s68, 0x360
	s_cselect_b64 s[2:3], -1, 0
	s_cmpk_gt_i32 s68, 0x35f
	v_readfirstlane_b32 s4, v10
	s_cbranch_scc1 .LBB0_1524
	s_ashr_i32 s5, s68, 31
	s_lshr_b32 s5, s5, 29
	s_add_i32 s5, s68, s5
	s_ashr_i32 s6, s5, 3
	s_and_b32 s5, s5, -8
	s_sub_i32 s5, s68, s5
	s_cmp_lt_i32 s5, 0
	s_movk_i32 s7, 0x6d
	s_cselect_b32 s7, s7, 0x6c
	s_mul_i32 s5, s7, s5
	s_add_i32 s5, s5, s6
	s_mul_hi_i32 s6, s5, 0x4bda12f7
	s_lshr_b32 s7, s6, 31
	s_ashr_i32 s6, s6, 3
	s_add_i32 s56, s6, s7
	s_mul_i32 s6, s56, 0xffffffe5
	s_add_i32 s6, s6, s5
	s_mul_hi_i32 s5, s6, 0x2aaaaaab
	s_lshr_b32 s7, s5, 31
	s_ashr_i32 s5, s5, 2
	s_add_i32 s5, s5, s7
	s_lshl_b32 s7, s5, 3
	s_sub_i32 s8, 9, s7
	s_min_i32 s8, s8, 8
	s_abs_i32 s9, s8
	v_cvt_f32_u32_e32 v2, s9
	s_sub_i32 s11, 0, s9
	s_mul_i32 s5, s5, 24
	s_sub_i32 s5, s6, s5
	v_rcp_iflag_f32_e32 v2, v2
	s_abs_i32 s10, s5
	s_xor_b32 s6, s5, s8
	s_ashr_i32 s6, s6, 31
	v_mul_f32_e32 v2, 0x4f7ffffe, v2
	v_cvt_u32_f32_e32 v2, v2
	s_nop 0
	v_readfirstlane_b32 s18, v2
	s_mul_i32 s11, s11, s18
	s_mul_hi_u32 s11, s18, s11
	s_add_i32 s18, s18, s11
	s_mul_hi_u32 s11, s10, s18
	s_mul_i32 s18, s11, s9
	s_sub_i32 s10, s10, s18
	s_add_i32 s18, s11, 1
	s_sub_i32 s19, s10, s9
	s_cmp_ge_u32 s10, s9
	s_cselect_b32 s11, s18, s11
	s_cselect_b32 s10, s19, s10
	s_add_i32 s18, s11, 1
	s_cmp_ge_u32 s10, s9
	s_cselect_b32 s9, s18, s11
	s_xor_b32 s9, s9, s6
	s_sub_i32 s57, s9, s6
	s_mul_i32 s6, s57, s8
	s_sub_i32 s5, s5, s6
	s_add_i32 s92, s5, s7
